# grid barrier poll interval s_sleep 4 instead of 1
# speedup vs baseline: 1.0076x; 1.0076x over previous
; __global__ void __launch_bounds__(NTH, 2) mega_kernel(Params p) {
;     ...
;   phase0a(p, smem);
;   wait_mod(p);
;   phase1(p);
;   phase0b(p, smem);
;   grid.sync();
.Lgs1_poll:
	global_load_dword v2, v0, s[6:7] offset:128 sc1
	s_waitcnt vmcnt(0)
	v_cmp_gt_u32_e32 vcc, s8, v2
	s_cbranch_vccz .Lgs1_done
	s_sleep 4
	s_branch .Lgs1_poll
